# HGRN2 core decay chain: exp(b_i) and exp(-b_i) carried as running f32 products of exp(lf_i) and exp(-lf_i) (2 transcendentals per row instead of 3, cumulative-sum adds dropped)
# speedup vs baseline: 1.0051x; 1.0051x over previous
; #define LAS __attribute__((address_space(3)))
; #define GAS __attribute__((address_space(1)))
; __device__ __forceinline__ bf16_t f2bf(float x) { return (bf16_t)(cvt_pk_bf16(x, x) & 0xffffu); }
; __device__ __forceinline__ float bf2f(bf16_t v) { return __uint_as_float((unsigned)v << 16); }
; __device__ __forceinline__ u32x4 pack8(const float* v) { u32x4 w; w.x = cvt_pk_bf16(v[0], v[1]); w.y = cvt_pk_bf16(v[2], v[3]); w.z = cvt_pk_bf16(v[4], v[5]); w.w = cvt_pk_bf16(v[6], v[7]); return w; }
; template <int DK, int DVS, bool RET> ...
;     ...
;                 for (int j = 0; j < 4; ++j) STB[(tv * 16 + quad * 4 + j) * LK + (kt0 + t) * 16 + l16] = f2bf(st[t][j]);
;             { const int p = tid >> 3, vg = tid & 7; const long row = R0 + (dir ? 63 - p : p); vraw = *(const GAS vvec_t*)(Vg + row * ldv + vcol0 + vg * VPT); }
;             float bl;
;             if constexpr (RET) {
;                 static_assert(!RET || DK == 256, "retention prep: 64 x 256 = 2048 eight-wide items, four per thread");
;                 bl = 64.f * lg;
; #pragma unroll
;                 for (int j = 0; j < 4; ++j) { const int it = tid + 512 * j, p = it & 63, k0 = (it >> 6) * 8; const float bb = (float)(p + 1) * lg;
;                     const float eq = __expf(bb), ek = __expf(-bb); float a[8], c[8];
; #pragma unroll
;                     for (int e = 0; e < 8; ++e) { a[e] = bf2f((bf16_t)qv[j][e]) * eq; c[e] = bf2f((bf16_t)kv[j][e]) * ek; }
;                     *(LAS u32x4*)(QD + p * LK + k0) = pack8(a); *(LAS u32x4*)(KD + p * LK + k0) = pack8(c); }
;             } else {
;                 float c = 0.f;
; #pragma unroll
;                 for (int i = 0; i < PPT; ++i) c += lc[i];
;                 TOT[pg * 128 + kx] = c;
;                 GLA_BAR();
;                 float off = 0.f; bl = 0.f;
; #pragma unroll
;                 for (int g = 0; g < NPG; ++g) { const float t = TOT[g * 128 + kx]; if (g < pg) off += t; bl += t; }
;                 float bb = off;
; #pragma unroll
;                 for (int i = 0; i < PPT; ++i) { const int p = pg * PPT + i;
;                     const float qf = bf2f(qr[i]), kf = 1.f - __expf(lc[i]); bb += lc[i];
;                     QD[p * LK + kx] = f2bf(qf * __expf(bb)); KD[p * LK + kx] = f2bf(kf * __expf(-bb)); }
.LBB0_54:
	v_cvt_pk_bf16_f32 v71, v71, s0
	s_waitcnt lgkmcnt(0)
	s_barrier
	ds_write_b16 v213, v71 offset:272
	v_cvt_pk_bf16_f32 v71, v72, s0
	s_waitcnt vmcnt(0)
	v_add_f32_e32 v72, 0, v132
	v_add_f32_e32 v72, v134, v72
	v_add_f32_e32 v72, v136, v72
	v_add_f32_e32 v72, v138, v72
	v_add_f32_e32 v72, v140, v72
	s_cmp_gt_u32 s36, 3
	v_add_f32_e32 v72, v142, v72
	s_cselect_b32 s40, 0x47, 3
	v_add_f32_e32 v72, v147, v72
	s_add_i32 s40, s40, s41
	v_add_f32_e32 v72, v151, v72
	s_and_b64 s[44:45], s[30:31], exec
	v_add_f32_e32 v72, v210, v72
	s_cselect_b32 s40, s36, s40
	v_add_f32_e32 v72, v220, v72
	s_lshl_b32 s40, s40, 6
	ds_write_b16 v213, v71 offset:544
	v_cvt_pk_bf16_f32 v71, v73, s0
	v_add_f32_e32 v72, v222, v72
	s_ashr_i32 s45, s40, 31
	ds_write_b16 v213, v71 offset:816
	v_cvt_pk_bf16_f32 v71, v74, s0
	v_add_f32_e32 v72, v224, v72
	ds_write_b16 v214, v71
	v_cvt_pk_bf16_f32 v71, v75, s0
	s_add_u32 s44, s42, s40
	v_add_f32_e32 v72, v226, v72
	ds_write_b16 v214, v71 offset:272
	v_cvt_pk_bf16_f32 v71, v234, s0
	v_cvt_pk_bf16_f32 v70, v70, s0
	s_addc_u32 s45, s43, s45
	v_add_f32_e32 v72, v228, v72
	ds_write_b16 v214, v71 offset:544
	ds_write_b16 v214, v70 offset:816
	v_lshl_add_u64 v[70:71], s[44:45], 0, v[56:57]
	v_add_f32_e32 v72, v230, v72
	v_cvt_pk_bf16_f32 v110, v0, s0
	v_lshlrev_b64 v[70:71], 11, v[70:71]
	v_add_f32_e32 v72, v232, v72
	ds_write_b16 v213, v110
	v_lshl_add_u64 v[70:71], v[58:59], 0, v[70:71]
	ds_write_b32 v152, v72
	global_load_dwordx2 v[70:71], v[70:71], off
	s_waitcnt lgkmcnt(0)
	s_barrier
	s_add_i32 s39, s36, 1
	s_min_i32 s39, s39, 0x43
	s_cmp_gt_u32 s39, 3
	s_cselect_b32 s38, 0x47, 3
	s_sub_i32 s38, s38, s39
	s_and_b64 s[54:55], s[30:31], exec
	s_cselect_b32 s38, s39, s38
	s_lshl_b32 s38, s38, 6
	s_ashr_i32 s39, s38, 31
	s_add_u32 s54, s42, s38
	s_addc_u32 s55, s43, s39
	s_lshl_b64 s[38:39], s[54:55], 11
	s_add_u32 s38, s38, s90
	s_addc_u32 s39, s39, s91
	s_lshl_b64 s[54:55], s[54:55], 13
	s_add_u32 s54, s54, s64
	s_addc_u32 s55, s55, s65
	ds_read2st64_b32 v[72:73], v153 offset1:2
	s_waitcnt lgkmcnt(0)
	v_add_f32_e32 v72, 0, v72
	v_cndmask_b32_e64 v74, 0, v72, s[6:7]
	v_add_f32_e32 v75, v73, v74
	v_cndmask_b32_e64 v110, v74, v75, s[8:9]
	ds_read2st64_b32 v[74:75], v153 offset0:4 offset1:6
	v_mul_f32_e32 v111, 0x3fb8aa3b, v132
	v_mul_f32_e32 v112, 0xbfb8aa3b, v132
	s_waitcnt lgkmcnt(0)
	v_add_f32_e32 v113, v74, v110
	v_cndmask_b32_e64 v110, v110, v113, s[10:11]
	v_add_f32_e32 v113, v75, v110
	v_cndmask_b32_e64 v110, v110, v113, s[12:13]
	v_mul_f32_e32 v113, 0xbfb8aa3b, v110
	v_mul_f32_e32 v110, 0x3fb8aa3b, v110
	v_exp_f32_e32 v113, v113
	v_exp_f32_e32 v110, v110
	global_load_dword v132, v20, s[54:55]
	v_exp_f32_e32 v111, v111
	v_exp_f32_e32 v112, v112
	v_mul_f32_e32 v110, v110, v111
	v_mul_f32_e32 v113, v113, v112
	v_sub_f32_e32 v111, 1.0, v111
	v_lshlrev_b32_e32 v112, 16, v133
	global_load_ushort v133, v21, s[38:39]
	v_mul_f32_e32 v111, v111, v113
	v_mul_f32_e32 v112, v110, v112
	v_cvt_pk_bf16_f32 v111, v111, s0
	v_cvt_pk_bf16_f32 v112, v112, s0
	ds_write_b16 v160, v112
	ds_write_b16 v161, v111
	v_mul_f32_e32 v111, 0x3fb8aa3b, v134
	v_mul_f32_e32 v112, 0xbfb8aa3b, v134
	global_load_dword v134, v26, s[54:55]
	v_exp_f32_e32 v111, v111
	v_exp_f32_e32 v112, v112
	v_mul_f32_e32 v110, v110, v111
	v_mul_f32_e32 v113, v113, v112
	v_sub_f32_e32 v111, 1.0, v111
	v_lshlrev_b32_e32 v112, 16, v135
	global_load_ushort v135, v27, s[38:39]
	v_mul_f32_e32 v111, v111, v113
	v_mul_f32_e32 v112, v110, v112
	v_cvt_pk_bf16_f32 v111, v111, s0
	v_cvt_pk_bf16_f32 v112, v112, s0
	ds_write_b16 v163, v112
	ds_write_b16 v164, v111
	v_mul_f32_e32 v111, 0x3fb8aa3b, v136
	v_mul_f32_e32 v112, 0xbfb8aa3b, v136
	global_load_dword v136, v28, s[54:55]
	v_exp_f32_e32 v111, v111
	v_exp_f32_e32 v112, v112
	v_mul_f32_e32 v110, v110, v111
	v_mul_f32_e32 v113, v113, v112
	v_sub_f32_e32 v111, 1.0, v111
	v_lshlrev_b32_e32 v112, 16, v137
	global_load_ushort v137, v29, s[38:39]
	v_mul_f32_e32 v111, v111, v113
	v_mul_f32_e32 v112, v110, v112
	v_cvt_pk_bf16_f32 v111, v111, s0
	v_cvt_pk_bf16_f32 v112, v112, s0
	ds_write_b16 v165, v112
	ds_write_b16 v166, v111
	v_mul_f32_e32 v111, 0x3fb8aa3b, v138
	v_mul_f32_e32 v112, 0xbfb8aa3b, v138
	global_load_dword v138, v30, s[54:55]
	v_exp_f32_e32 v111, v111
	v_exp_f32_e32 v112, v112
	v_mul_f32_e32 v110, v110, v111
	v_mul_f32_e32 v113, v113, v112
	v_sub_f32_e32 v111, 1.0, v111
	v_lshlrev_b32_e32 v112, 16, v139
	global_load_ushort v139, v31, s[38:39]
	v_mul_f32_e32 v111, v111, v113
	v_mul_f32_e32 v112, v110, v112
	v_cvt_pk_bf16_f32 v111, v111, s0
	v_cvt_pk_bf16_f32 v112, v112, s0
	ds_write_b16 v167, v112
	ds_write_b16 v168, v111
	v_mul_f32_e32 v111, 0x3fb8aa3b, v140
	v_mul_f32_e32 v112, 0xbfb8aa3b, v140
	global_load_dword v140, v32, s[54:55]
	v_exp_f32_e32 v111, v111
	v_exp_f32_e32 v112, v112
	v_mul_f32_e32 v110, v110, v111
	v_mul_f32_e32 v113, v113, v112
	v_sub_f32_e32 v111, 1.0, v111
	v_lshlrev_b32_e32 v112, 16, v141
	global_load_ushort v141, v33, s[38:39]
	v_mul_f32_e32 v111, v111, v113
	v_mul_f32_e32 v112, v110, v112
	v_cvt_pk_bf16_f32 v111, v111, s0
	v_cvt_pk_bf16_f32 v112, v112, s0
	ds_write_b16 v169, v112
	ds_write_b16 v170, v111
	v_mul_f32_e32 v111, 0x3fb8aa3b, v142
	v_mul_f32_e32 v112, 0xbfb8aa3b, v142
	global_load_dword v142, v34, s[54:55]
	v_exp_f32_e32 v111, v111
	v_exp_f32_e32 v112, v112
	v_mul_f32_e32 v110, v110, v111
	v_mul_f32_e32 v113, v113, v112
	v_sub_f32_e32 v111, 1.0, v111
	v_lshlrev_b32_e32 v112, 16, v143
	global_load_ushort v143, v35, s[38:39]
	v_mul_f32_e32 v111, v111, v113
	v_mul_f32_e32 v112, v110, v112
; #define LAS __attribute__((address_space(3)))
; __device__ __forceinline__ bf16_t f2bf(float x) { return (bf16_t)(cvt_pk_bf16(x, x) & 0xffffu); }
; __device__ __forceinline__ float bf2f(bf16_t v) { return __uint_as_float((unsigned)v << 16); }
; template <int DK, int DVS, bool RET> ...
;     ...
;                 float bb = off;
; #pragma unroll
;                 for (int i = 0; i < PPT; ++i) { const int p = pg * PPT + i;
;                     const float qf = bf2f(qr[i]), kf = 1.f - __expf(lc[i]); bb += lc[i];
;                     QD[p * LK + kx] = f2bf(qf * __expf(bb)); KD[p * LK + kx] = f2bf(kf * __expf(-bb)); }
;             }
;             if (pg == 0) EL[kx] = __expf(bl);
;             { const int p = tid >> 3, vg = tid & 7; *(LAS vvec_t*)(VI + p * LV + vg * VPT) = vraw; }
	v_cvt_pk_bf16_f32 v111, v111, s0
	v_cvt_pk_bf16_f32 v112, v112, s0
	ds_write_b16 v171, v112
	ds_write_b16 v172, v111
	v_mul_f32_e32 v111, 0x3fb8aa3b, v147
	v_mul_f32_e32 v112, 0xbfb8aa3b, v147
	global_load_dword v147, v36, s[54:55]
	v_exp_f32_e32 v111, v111
	v_exp_f32_e32 v112, v112
	v_mul_f32_e32 v110, v110, v111
	v_mul_f32_e32 v113, v113, v112
	v_sub_f32_e32 v111, 1.0, v111
	v_lshlrev_b32_e32 v112, 16, v150
	global_load_ushort v150, v37, s[38:39]
	v_mul_f32_e32 v111, v111, v113
	v_mul_f32_e32 v112, v110, v112
	v_cvt_pk_bf16_f32 v111, v111, s0
	v_cvt_pk_bf16_f32 v112, v112, s0
	ds_write_b16 v173, v112
	ds_write_b16 v174, v111
	v_mul_f32_e32 v111, 0x3fb8aa3b, v151
	v_mul_f32_e32 v112, 0xbfb8aa3b, v151
	global_load_dword v151, v38, s[54:55]
	v_exp_f32_e32 v111, v111
	v_exp_f32_e32 v112, v112
	v_mul_f32_e32 v110, v110, v111
	v_mul_f32_e32 v113, v113, v112
	v_sub_f32_e32 v111, 1.0, v111
	v_lshlrev_b32_e32 v112, 16, v162
	global_load_ushort v162, v39, s[38:39]
	v_mul_f32_e32 v111, v111, v113
	v_mul_f32_e32 v112, v110, v112
	v_cvt_pk_bf16_f32 v111, v111, s0
	v_cvt_pk_bf16_f32 v112, v112, s0
	ds_write_b16 v175, v112
	ds_write_b16 v176, v111
	v_mul_f32_e32 v111, 0x3fb8aa3b, v210
	v_mul_f32_e32 v112, 0xbfb8aa3b, v210
	global_load_dword v210, v40, s[54:55]
	v_exp_f32_e32 v111, v111
	v_exp_f32_e32 v112, v112
	v_mul_f32_e32 v110, v110, v111
	v_mul_f32_e32 v113, v113, v112
	v_sub_f32_e32 v111, 1.0, v111
	v_lshlrev_b32_e32 v112, 16, v217
	global_load_ushort v217, v41, s[38:39]
	v_mul_f32_e32 v111, v111, v113
	v_mul_f32_e32 v112, v110, v112
	v_cvt_pk_bf16_f32 v111, v111, s0
	v_cvt_pk_bf16_f32 v112, v112, s0
	ds_write_b16 v177, v112
	ds_write_b16 v178, v111
	v_mul_f32_e32 v111, 0x3fb8aa3b, v220
	v_mul_f32_e32 v112, 0xbfb8aa3b, v220
	global_load_dword v220, v42, s[54:55]
	v_exp_f32_e32 v111, v111
	v_exp_f32_e32 v112, v112
	v_mul_f32_e32 v110, v110, v111
	v_mul_f32_e32 v113, v113, v112
	v_sub_f32_e32 v111, 1.0, v111
	v_lshlrev_b32_e32 v112, 16, v221
	global_load_ushort v221, v43, s[38:39]
	v_mul_f32_e32 v111, v111, v113
	v_mul_f32_e32 v112, v110, v112
	v_cvt_pk_bf16_f32 v111, v111, s0
	v_cvt_pk_bf16_f32 v112, v112, s0
	ds_write_b16 v179, v112
	ds_write_b16 v180, v111
	v_mul_f32_e32 v111, 0x3fb8aa3b, v222
	v_mul_f32_e32 v112, 0xbfb8aa3b, v222
	global_load_dword v222, v44, s[54:55]
	v_exp_f32_e32 v111, v111
	v_exp_f32_e32 v112, v112
	v_mul_f32_e32 v110, v110, v111
	v_mul_f32_e32 v113, v113, v112
	v_sub_f32_e32 v111, 1.0, v111
	v_lshlrev_b32_e32 v112, 16, v223
	global_load_ushort v223, v45, s[38:39]
	v_mul_f32_e32 v111, v111, v113
	v_mul_f32_e32 v112, v110, v112
	v_cvt_pk_bf16_f32 v111, v111, s0
	v_cvt_pk_bf16_f32 v112, v112, s0
	ds_write_b16 v181, v112
	ds_write_b16 v182, v111
	v_mul_f32_e32 v111, 0x3fb8aa3b, v224
	v_mul_f32_e32 v112, 0xbfb8aa3b, v224
	global_load_dword v224, v46, s[54:55]
	v_exp_f32_e32 v111, v111
	v_exp_f32_e32 v112, v112
	v_mul_f32_e32 v110, v110, v111
	v_mul_f32_e32 v113, v113, v112
	v_sub_f32_e32 v111, 1.0, v111
	v_lshlrev_b32_e32 v112, 16, v225
	global_load_ushort v225, v47, s[38:39]
	v_mul_f32_e32 v111, v111, v113
	v_mul_f32_e32 v112, v110, v112
	v_cvt_pk_bf16_f32 v111, v111, s0
	v_cvt_pk_bf16_f32 v112, v112, s0
	ds_write_b16 v183, v112
	ds_write_b16 v184, v111
	v_mul_f32_e32 v111, 0x3fb8aa3b, v226
	v_mul_f32_e32 v112, 0xbfb8aa3b, v226
	global_load_dword v226, v48, s[54:55]
	v_exp_f32_e32 v111, v111
	v_exp_f32_e32 v112, v112
	v_mul_f32_e32 v110, v110, v111
	v_mul_f32_e32 v113, v113, v112
	v_sub_f32_e32 v111, 1.0, v111
	v_lshlrev_b32_e32 v112, 16, v227
	global_load_ushort v227, v49, s[38:39]
	v_mul_f32_e32 v111, v111, v113
	v_mul_f32_e32 v112, v110, v112
	v_cvt_pk_bf16_f32 v111, v111, s0
	v_cvt_pk_bf16_f32 v112, v112, s0
	ds_write_b16 v185, v112
	ds_write_b16 v199, v111
	v_mul_f32_e32 v111, 0x3fb8aa3b, v228
	v_mul_f32_e32 v112, 0xbfb8aa3b, v228
	global_load_dword v228, v50, s[54:55]
	v_exp_f32_e32 v111, v111
	v_exp_f32_e32 v112, v112
	v_mul_f32_e32 v110, v110, v111
	v_mul_f32_e32 v113, v113, v112
	v_sub_f32_e32 v111, 1.0, v111
	v_lshlrev_b32_e32 v112, 16, v229
	global_load_ushort v229, v51, s[38:39]
	v_mul_f32_e32 v111, v111, v113
	v_mul_f32_e32 v112, v110, v112
	v_cvt_pk_bf16_f32 v111, v111, s0
	v_cvt_pk_bf16_f32 v112, v112, s0
	ds_write_b16 v200, v112
	ds_write_b16 v201, v111
	v_mul_f32_e32 v111, 0x3fb8aa3b, v230
	v_mul_f32_e32 v112, 0xbfb8aa3b, v230
	global_load_dword v230, v52, s[54:55]
	v_exp_f32_e32 v111, v111
	v_exp_f32_e32 v112, v112
	v_mul_f32_e32 v110, v110, v111
	v_mul_f32_e32 v113, v113, v112
	v_sub_f32_e32 v111, 1.0, v111
	v_lshlrev_b32_e32 v112, 16, v231
	global_load_ushort v231, v53, s[38:39]
	v_mul_f32_e32 v111, v111, v113
	v_mul_f32_e32 v112, v110, v112
	v_cvt_pk_bf16_f32 v111, v111, s0
	v_cvt_pk_bf16_f32 v112, v112, s0
	ds_write_b16 v202, v112
	ds_write_b16 v203, v111
	v_mul_f32_e32 v111, 0x3fb8aa3b, v232
	v_mul_f32_e32 v112, 0xbfb8aa3b, v232
	global_load_dword v232, v54, s[54:55]
	v_exp_f32_e32 v111, v111
	v_exp_f32_e32 v112, v112
	v_mul_f32_e32 v110, v110, v111
	v_mul_f32_e32 v113, v113, v112
	v_sub_f32_e32 v111, 1.0, v111
	v_lshlrev_b32_e32 v112, 16, v233
	global_load_ushort v233, v55, s[38:39]
	v_mul_f32_e32 v111, v111, v113
	v_mul_f32_e32 v112, v110, v112
	v_cvt_pk_bf16_f32 v111, v111, s0
	v_cvt_pk_bf16_f32 v112, v112, s0
	ds_write_b16 v204, v112
	ds_write_b16 v205, v111
	s_and_saveexec_b64 s[46:47], vcc
	s_cbranch_execz .LBB0_56
	v_add_f32_e32 v72, v72, v73
	v_add_f32_e32 v72, v72, v74
	v_add_f32_e32 v72, v72, v75
	v_mul_f32_e32 v72, 0x3fb8aa3b, v72
	v_exp_f32_e32 v72, v72
	ds_write_b32 v154, v72
